# best_b + scheduler shift/mask + batched mixer segment-4 parameter loads + v_cvt_pk_bf16_f32 in the norm phases (stack of individually neutral edits)
# speedup vs baseline: 1.0074x; 1.0074x over previous
.LBB0_182:
	v_mul_f32_e32 v84, v45, v45
	v_mul_f32_e32 v85, v47, v47
	v_fmac_f32_e32 v84, v44, v44
	v_fmac_f32_e32 v85, v46, v46
	v_add_f32_e32 v84, v84, v85
	v_mul_f32_e32 v85, v25, v25
	v_mul_f32_e32 v86, v27, v27
	v_fmac_f32_e32 v85, v24, v24
	v_fmac_f32_e32 v86, v26, v26
	v_add_f32_e32 v85, v85, v86
	v_add_f32_e32 v84, v84, v85
	v_mul_f32_e32 v85, v21, v21
	v_mul_f32_e32 v86, v23, v23
	v_fmac_f32_e32 v85, v20, v20
	v_fmac_f32_e32 v86, v22, v22
	v_add_f32_e32 v85, v85, v86
	v_add_f32_e32 v84, v85, v84
	v_mul_f32_e32 v85, v17, v17
	v_mul_f32_e32 v86, v19, v19
	v_fmac_f32_e32 v85, v16, v16
	v_fmac_f32_e32 v86, v18, v18
	v_add_f32_e32 v85, v85, v86
	v_add_f32_e32 v84, v85, v84
	ds_bpermute_b32 v85, v72, v84
	s_waitcnt lgkmcnt(0)
	v_add_f32_e32 v84, v84, v85
	ds_bpermute_b32 v85, v73, v84
	s_waitcnt lgkmcnt(0)
	v_add_f32_e32 v84, v84, v85
	ds_bpermute_b32 v85, v74, v84
	s_waitcnt lgkmcnt(0)
	v_add_f32_e32 v84, v84, v85
	ds_bpermute_b32 v85, v75, v84
	s_waitcnt lgkmcnt(0)
	v_add_f32_e32 v84, v84, v85
	ds_bpermute_b32 v85, v76, v84
	s_waitcnt lgkmcnt(0)
	v_add_f32_e32 v84, v84, v85
	ds_bpermute_b32 v85, v77, v84
	s_waitcnt lgkmcnt(0)
	v_add_f32_e32 v84, v84, v85
	v_fmamk_f32 v84, v84, 0x3a800000, v82
	v_mul_f32_e32 v85, 0x4f800000, v84
	v_cmp_gt_f32_e32 vcc, s3, v84
	s_nop 1
	v_cndmask_b32_e32 v84, v84, v85, vcc
	v_sqrt_f32_e32 v85, v84
	s_nop 0
	v_add_u32_e32 v86, -1, v85
	v_add_u32_e32 v87, 1, v85
	v_fma_f32 v88, -v86, v85, v84
	v_fma_f32 v89, -v87, v85, v84
	v_cmp_ge_f32_e64 s[0:1], 0, v88
	s_nop 1
	v_cndmask_b32_e64 v85, v85, v86, s[0:1]
	v_cmp_lt_f32_e64 s[0:1], 0, v89
	s_nop 1
	v_cndmask_b32_e64 v85, v85, v87, s[0:1]
	v_mul_f32_e32 v86, 0x37800000, v85
	v_cndmask_b32_e32 v85, v85, v86, vcc
	v_cmp_class_f32_e32 vcc, v84, v83
	s_nop 1
	v_cndmask_b32_e32 v84, v85, v84, vcc
	v_div_scale_f32 v85, s[0:1], v84, v84, 1.0
	v_rcp_f32_e32 v86, v85
	v_div_scale_f32 v87, vcc, 1.0, v84, 1.0
	v_fma_f32 v88, -v85, v86, 1.0
	v_fmac_f32_e32 v86, v88, v86
	v_mul_f32_e32 v88, v87, v86
	v_fma_f32 v89, -v85, v88, v87
	v_fmac_f32_e32 v88, v89, v86
	v_fma_f32 v85, -v85, v88, v87
	v_div_fmas_f32 v85, v85, v86, v88
	v_div_fixup_f32 v84, v85, v84, 1.0
	v_pk_mul_f32 v[44:45], v[44:45], v[84:85] op_sel_hi:[1,0]
	v_pk_mul_f32 v[46:47], v[46:47], v[84:85] op_sel_hi:[1,0]
	v_pk_fma_f32 v[44:45], v[58:59], v[44:45], v[0:1]
	v_pk_fma_f32 v[46:47], v[56:57], v[46:47], v[2:3]
	v_bfe_u32 v85, v44, 16, 1
	v_bfe_u32 v86, v45, 16, 1
	v_add3_u32 v44, v44, v85, s18
	v_lshrrev_b32_e32 v44, 16, v44
	v_add3_u32 v45, v45, v86, s18
	v_and_or_b32 v44, v45, s19, v44
	v_pk_mul_f32 v[24:25], v[24:25], v[84:85] op_sel_hi:[1,0]
	v_cvt_pk_bf16_f32 v45, v46, v47
	v_pk_fma_f32 v[24:25], v[62:63], v[24:25], v[4:5]
	global_store_dwordx2 v[54:55], v[44:45], off offset:-1024
	v_bfe_u32 v44, v24, 16, 1
	v_pk_mul_f32 v[26:27], v[26:27], v[84:85] op_sel_hi:[1,0]
	v_add3_u32 v24, v24, v44, s18
	v_bfe_u32 v44, v25, 16, 1
	v_pk_fma_f32 v[26:27], v[60:61], v[26:27], v[6:7]
	v_lshrrev_b32_e32 v24, 16, v24
	v_add3_u32 v25, v25, v44, s18
	v_and_or_b32 v24, v25, s19, v24
	v_pk_mul_f32 v[20:21], v[20:21], v[84:85] op_sel_hi:[1,0]
	v_cvt_pk_bf16_f32 v25, v26, v27
	v_pk_fma_f32 v[20:21], v[66:67], v[20:21], v[8:9]
	global_store_dwordx2 v[54:55], v[24:25], off offset:-512
	v_bfe_u32 v24, v20, 16, 1
	v_pk_mul_f32 v[22:23], v[22:23], v[84:85] op_sel_hi:[1,0]
	v_add3_u32 v20, v20, v24, s18
	v_bfe_u32 v24, v21, 16, 1
	v_pk_fma_f32 v[22:23], v[64:65], v[22:23], v[10:11]
	v_lshrrev_b32_e32 v20, 16, v20
	v_add3_u32 v21, v21, v24, s18
	v_and_or_b32 v20, v21, s19, v20
	v_pk_mul_f32 v[16:17], v[16:17], v[84:85] op_sel_hi:[1,0]
	v_cvt_pk_bf16_f32 v21, v22, v23
	v_pk_fma_f32 v[16:17], v[70:71], v[16:17], v[12:13]
	global_store_dwordx2 v[54:55], v[20:21], off
	v_bfe_u32 v20, v16, 16, 1
	v_pk_mul_f32 v[18:19], v[18:19], v[84:85] op_sel_hi:[1,0]
	v_add3_u32 v16, v16, v20, s18
	v_bfe_u32 v20, v17, 16, 1
	v_pk_fma_f32 v[18:19], v[68:69], v[18:19], v[14:15]
	v_lshrrev_b32_e32 v16, 16, v16
	v_add3_u32 v17, v17, v20, s18
	v_and_or_b32 v16, v17, s19, v16
	v_cvt_pk_bf16_f32 v17, v18, v19
	global_store_dwordx2 v[54:55], v[16:17], off offset:512
	v_lshl_add_u64 v[54:55], v[54:55], 0, s[6:7]
	s_and_b64 vcc, exec, s[16:17]
	s_waitcnt vmcnt(7)
	v_mov_b32_e32 v44, v28
	v_mov_b32_e32 v45, v29
	v_mov_b32_e32 v46, v30
	v_mov_b32_e32 v47, v31
	s_waitcnt vmcnt(6)
	v_mov_b32_e32 v24, v32
	v_mov_b32_e32 v25, v33
	v_mov_b32_e32 v26, v34
	v_mov_b32_e32 v27, v35
	s_waitcnt vmcnt(5)
	v_mov_b32_e32 v20, v36
	v_mov_b32_e32 v21, v37
	v_mov_b32_e32 v22, v38
	v_mov_b32_e32 v23, v39
	s_waitcnt vmcnt(4)
	v_mov_b32_e32 v16, v40
	v_mov_b32_e32 v17, v41
	v_mov_b32_e32 v18, v42
	v_mov_b32_e32 v19, v43
	s_cbranch_vccnz .LBB0_180

.LBB0_404:
	v_mul_f32_e32 v206, v173, v173
	v_mul_f32_e32 v207, v175, v175
	v_fmac_f32_e32 v206, v172, v172
	v_fmac_f32_e32 v207, v174, v174
	v_add_f32_e32 v206, v206, v207
	v_mul_f32_e32 v207, v169, v169
	v_mul_f32_e32 v223, v171, v171
	v_fmac_f32_e32 v207, v168, v168
	v_fmac_f32_e32 v223, v170, v170
	v_add_f32_e32 v207, v207, v223
	v_add_f32_e32 v206, v207, v206
	v_mul_f32_e32 v207, v165, v165
	v_mul_f32_e32 v223, v167, v167
	v_fmac_f32_e32 v207, v164, v164
	v_fmac_f32_e32 v223, v166, v166
	v_add_f32_e32 v207, v207, v223
	v_add_f32_e32 v206, v207, v206
	v_mul_f32_e32 v207, v161, v161
	v_mul_f32_e32 v223, v163, v163
	v_fmac_f32_e32 v207, v160, v160
	v_fmac_f32_e32 v223, v162, v162
	v_add_f32_e32 v207, v207, v223
	v_add_f32_e32 v206, v207, v206
	ds_bpermute_b32 v207, v209, v206
	s_waitcnt lgkmcnt(0)
	v_add_f32_e32 v206, v206, v207
	ds_bpermute_b32 v207, v211, v206
	s_waitcnt lgkmcnt(0)
	v_add_f32_e32 v206, v206, v207
	ds_bpermute_b32 v207, v212, v206
	s_waitcnt lgkmcnt(0)
	v_add_f32_e32 v206, v206, v207
	ds_bpermute_b32 v207, v213, v206
	s_waitcnt lgkmcnt(0)
	v_add_f32_e32 v206, v206, v207
	ds_bpermute_b32 v207, v214, v206
	s_waitcnt lgkmcnt(0)
	v_add_f32_e32 v206, v206, v207
	ds_bpermute_b32 v207, v215, v206
	s_waitcnt lgkmcnt(0)
	v_add_f32_e32 v206, v206, v207
	v_fmamk_f32 v206, v206, 0x3a800000, v220
	v_mul_f32_e32 v207, 0x4f800000, v206
	v_cmp_gt_f32_e32 vcc, s25, v206
	s_nop 1
	v_cndmask_b32_e32 v206, v206, v207, vcc
	v_sqrt_f32_e32 v207, v206
	s_nop 0
	v_add_u32_e32 v223, -1, v207
	v_add_u32_e32 v224, 1, v207
	v_fma_f32 v225, -v223, v207, v206
	v_fma_f32 v226, -v224, v207, v206
	v_cmp_ge_f32_e64 s[0:1], 0, v225
	s_nop 1
	v_cndmask_b32_e64 v207, v207, v223, s[0:1]
	v_cmp_lt_f32_e64 s[0:1], 0, v226
	s_nop 1
	v_cndmask_b32_e64 v207, v207, v224, s[0:1]
	v_mul_f32_e32 v223, 0x37800000, v207
	v_cndmask_b32_e32 v207, v207, v223, vcc
	v_cmp_class_f32_e32 vcc, v206, v221
	s_nop 1
	v_cndmask_b32_e32 v206, v207, v206, vcc
	v_div_scale_f32 v207, s[0:1], v206, v206, 1.0
	v_rcp_f32_e32 v223, v207
	v_div_scale_f32 v224, vcc, 1.0, v206, 1.0
	v_fma_f32 v225, -v207, v223, 1.0
	v_fmac_f32_e32 v223, v225, v223
	v_mul_f32_e32 v225, v224, v223
	v_fma_f32 v226, -v207, v225, v224
	v_fmac_f32_e32 v225, v226, v223
	v_fma_f32 v207, -v207, v225, v224
	v_div_fmas_f32 v207, v207, v223, v225
	v_div_fixup_f32 v206, v207, v206, 1.0
	v_pk_mul_f32 v[224:225], v[172:173], v[206:207] op_sel_hi:[1,0]
	v_pk_mul_f32 v[172:173], v[174:175], v[206:207] op_sel_hi:[1,0]
	v_pk_fma_f32 v[174:175], v[192:193], v[224:225], v[128:129]
	v_pk_fma_f32 v[172:173], v[190:191], v[172:173], v[130:131]
	v_cvt_pk_bf16_f32 v224, v174, v175
	v_cvt_pk_bf16_f32 v225, v172, v173
	global_store_dwordx2 v[186:187], v[224:225], off offset:-1024
	v_pk_mul_f32 v[224:225], v[168:169], v[206:207] op_sel_hi:[1,0]
	v_pk_mul_f32 v[168:169], v[170:171], v[206:207] op_sel_hi:[1,0]
	v_pk_fma_f32 v[170:171], v[196:197], v[224:225], v[132:133]
	v_pk_fma_f32 v[168:169], v[194:195], v[168:169], v[134:135]
	v_cvt_pk_bf16_f32 v224, v170, v171
	v_cvt_pk_bf16_f32 v225, v168, v169
	global_store_dwordx2 v[186:187], v[224:225], off offset:-512
	v_pk_mul_f32 v[224:225], v[164:165], v[206:207] op_sel_hi:[1,0]
	v_pk_mul_f32 v[164:165], v[166:167], v[206:207] op_sel_hi:[1,0]
	s_waitcnt vmcnt(3)
	v_pk_fma_f32 v[166:167], v[200:201], v[224:225], v[136:137]
	v_pk_fma_f32 v[164:165], v[198:199], v[164:165], v[138:139]
	v_cvt_pk_bf16_f32 v224, v166, v167
	v_cvt_pk_bf16_f32 v225, v164, v165
	v_pk_mul_f32 v[226:227], v[160:161], v[206:207] op_sel_hi:[1,0]
	v_pk_mul_f32 v[160:161], v[162:163], v[206:207] op_sel_hi:[1,0]
	v_mul_f32_e32 v206, v1, v175
	v_mul_f32_e32 v207, v3, v173
	v_fmac_f32_e32 v206, v0, v174
	v_fmac_f32_e32 v207, v2, v172
	v_add_f32_e32 v206, v206, v207
	v_mul_f32_e32 v207, v5, v171
	v_mul_f32_e32 v223, v7, v169
	v_fmac_f32_e32 v207, v4, v170
	v_fmac_f32_e32 v223, v6, v168
	v_add_f32_e32 v206, 0, v206
	v_add_f32_e32 v207, v207, v223
	v_add_f32_e32 v206, v207, v206
	v_mul_f32_e32 v207, v9, v167
	v_mul_f32_e32 v223, v11, v165
	v_fmac_f32_e32 v207, v8, v166
	v_fmac_f32_e32 v223, v10, v164
	s_waitcnt vmcnt(2)
	v_pk_fma_f32 v[160:161], v[202:203], v[160:161], v[142:143]
	v_pk_fma_f32 v[162:163], v[204:205], v[226:227], v[140:141]
	v_add_f32_e32 v207, v207, v223
	v_add_f32_e32 v206, v207, v206
	v_mul_f32_e32 v207, v13, v163
	v_mul_f32_e32 v223, v15, v161
	v_fmac_f32_e32 v207, v12, v162
	v_fmac_f32_e32 v223, v14, v160
	v_add_f32_e32 v207, v207, v223
	v_mul_f32_e32 v223, v175, v17
	v_mul_f32_e32 v226, v173, v19
	v_fmac_f32_e32 v223, v174, v16
	v_fmac_f32_e32 v226, v172, v18
	v_add_f32_e32 v223, v223, v226
	v_mul_f32_e32 v226, v171, v21
	v_mul_f32_e32 v227, v169, v23
	v_fmac_f32_e32 v226, v170, v20
	v_fmac_f32_e32 v227, v168, v22
	v_add_f32_e32 v223, 0, v223
	v_add_f32_e32 v226, v226, v227
	v_add_f32_e32 v223, v223, v226
	v_mul_f32_e32 v226, v167, v25
	v_mul_f32_e32 v227, v165, v27
	v_fmac_f32_e32 v226, v166, v24
	v_fmac_f32_e32 v227, v164, v26
	v_add_f32_e32 v226, v226, v227
	v_add_f32_e32 v223, v223, v226
	v_mul_f32_e32 v226, v163, v29
	v_mul_f32_e32 v227, v161, v31
	v_fmac_f32_e32 v226, v162, v28
	v_fmac_f32_e32 v227, v160, v30
	v_add_f32_e32 v226, v226, v227
	v_add_f32_e32 v206, v207, v206
	v_add_f32_e32 v223, v223, v226
	ds_bpermute_b32 v207, v209, v206
	ds_bpermute_b32 v226, v209, v223
	global_store_dwordx2 v[186:187], v[224:225], off
	v_bfe_u32 v224, v162, 16, 1
	v_add3_u32 v224, v162, v224, s42
	s_waitcnt lgkmcnt(1)
	v_add_f32_e32 v206, v206, v207
	s_waitcnt lgkmcnt(0)
	v_add_f32_e32 v223, v223, v226
	ds_bpermute_b32 v207, v211, v206
	ds_bpermute_b32 v225, v211, v223
	v_bfe_u32 v226, v163, 16, 1
	v_lshrrev_b32_e32 v224, 16, v224
	v_add3_u32 v226, v163, v226, s42
	s_waitcnt lgkmcnt(1)
	v_add_f32_e32 v206, v206, v207
	s_waitcnt lgkmcnt(0)
	v_add_f32_e32 v223, v223, v225
	ds_bpermute_b32 v207, v212, v206
	ds_bpermute_b32 v225, v212, v223
	v_mul_f32_e32 v228, v169, v39
	v_fmac_f32_e32 v228, v168, v38
	v_mul_f32_e32 v229, v173, v51
	s_waitcnt lgkmcnt(1)
	v_add_f32_e32 v207, v206, v207
	s_waitcnt lgkmcnt(0)
	v_add_f32_e32 v223, v223, v225
	ds_bpermute_b32 v227, v213, v207
	ds_bpermute_b32 v225, v213, v223
	v_and_or_b32 v206, v226, s43, v224
	v_bfe_u32 v224, v160, 16, 1
	v_fmac_f32_e32 v229, v172, v50
	s_waitcnt lgkmcnt(1)
	v_add_f32_e32 v207, v207, v227
	s_waitcnt lgkmcnt(0)
	v_add_f32_e32 v225, v223, v225
	ds_bpermute_b32 v226, v214, v207
	ds_bpermute_b32 v227, v214, v225
	v_add3_u32 v223, v160, v224, s42
	v_lshrrev_b32_e32 v233, 16, v223
	v_mul_f32_e32 v230, v169, v55
	s_waitcnt lgkmcnt(1)
	v_add_f32_e32 v223, v207, v226
	s_waitcnt lgkmcnt(0)
	v_add_f32_e32 v225, v225, v227
	v_mul_f32_e32 v207, v175, v33
	v_mul_f32_e32 v227, v173, v35
	v_fmac_f32_e32 v207, v174, v32
	v_fmac_f32_e32 v227, v172, v34
	v_add_f32_e32 v207, v207, v227
	v_mul_f32_e32 v227, v171, v37
	v_fmac_f32_e32 v227, v170, v36
	v_add_f32_e32 v207, 0, v207
	v_add_f32_e32 v227, v227, v228
	v_add_f32_e32 v207, v207, v227
	v_mul_f32_e32 v227, v167, v41
	v_mul_f32_e32 v228, v165, v43
	v_fmac_f32_e32 v227, v166, v40
	v_fmac_f32_e32 v228, v164, v42
	v_add_f32_e32 v227, v227, v228
	v_add_f32_e32 v207, v207, v227
	v_mul_f32_e32 v227, v163, v45
	v_mul_f32_e32 v228, v161, v47
	v_fmac_f32_e32 v227, v162, v44
	v_fmac_f32_e32 v228, v160, v46
	v_add_f32_e32 v227, v227, v228
	v_mul_f32_e32 v228, v175, v49
	v_fmac_f32_e32 v228, v174, v48
	v_add_f32_e32 v228, v228, v229
	v_mul_f32_e32 v229, v171, v53
	v_fmac_f32_e32 v229, v170, v52
	v_fmac_f32_e32 v230, v168, v54
	v_add_f32_e32 v228, 0, v228
	v_add_f32_e32 v229, v229, v230
	v_add_f32_e32 v228, v228, v229
	v_mul_f32_e32 v229, v167, v57
	v_mul_f32_e32 v230, v165, v59
	v_fmac_f32_e32 v229, v166, v56
	v_fmac_f32_e32 v230, v164, v58
	v_add_f32_e32 v229, v229, v230
	v_add_f32_e32 v228, v228, v229
	v_mul_f32_e32 v229, v163, v61
	v_mul_f32_e32 v230, v161, v63
	v_fmac_f32_e32 v229, v162, v60
	v_fmac_f32_e32 v230, v160, v62
	v_add_f32_e32 v229, v229, v230
	v_mul_f32_e32 v230, v175, v65
	v_mul_f32_e32 v231, v173, v67
	v_fmac_f32_e32 v230, v174, v64
	v_fmac_f32_e32 v231, v172, v66
	v_add_f32_e32 v230, v230, v231
	v_mul_f32_e32 v231, v171, v69
	v_mul_f32_e32 v232, v169, v71
	v_fmac_f32_e32 v231, v170, v68
	v_fmac_f32_e32 v232, v168, v70
	v_add_f32_e32 v230, 0, v230
	v_add_f32_e32 v231, v231, v232
	v_add_f32_e32 v230, v230, v231
	v_mul_f32_e32 v231, v167, v73
	v_mul_f32_e32 v232, v165, v75
	v_fmac_f32_e32 v231, v166, v72
	v_fmac_f32_e32 v232, v164, v74
	v_add_f32_e32 v231, v231, v232
	v_add_f32_e32 v230, v230, v231
	v_mul_f32_e32 v231, v163, v77
	v_mul_f32_e32 v232, v161, v79
	v_fmac_f32_e32 v231, v162, v76
	v_fmac_f32_e32 v232, v160, v78
	v_add_f32_e32 v231, v231, v232
	v_add_f32_e32 v207, v207, v227
	v_add_f32_e32 v230, v230, v231
	ds_bpermute_b32 v227, v209, v207
	ds_bpermute_b32 v231, v209, v230
	v_mul_f32_e32 v235, v169, v87
	v_fmac_f32_e32 v235, v168, v86
	v_mul_f32_e32 v236, v173, v99
	s_waitcnt lgkmcnt(1)
	v_add_f32_e32 v207, v207, v227
	s_waitcnt lgkmcnt(0)
	v_add_f32_e32 v230, v230, v231
	ds_bpermute_b32 v227, v211, v207
	ds_bpermute_b32 v231, v211, v230
	v_fmac_f32_e32 v236, v172, v98
	v_mul_f32_e32 v237, v169, v103
	v_fmac_f32_e32 v237, v168, v102
	s_waitcnt lgkmcnt(1)
	v_add_f32_e32 v207, v207, v227
	s_waitcnt lgkmcnt(0)
	v_add_f32_e32 v230, v230, v231
	ds_bpermute_b32 v227, v212, v207
	ds_bpermute_b32 v231, v212, v230
	v_mul_f32_e32 v169, v169, v119
	v_fmac_f32_e32 v169, v168, v118
	v_add_f32_e32 v228, v228, v229
	s_waitcnt lgkmcnt(1)
	v_add_f32_e32 v207, v207, v227
	s_waitcnt lgkmcnt(0)
	v_add_f32_e32 v230, v230, v231
	ds_bpermute_b32 v227, v213, v207
	ds_bpermute_b32 v231, v213, v230
	ds_bpermute_b32 v229, v209, v228
	ds_bpermute_b32 v224, v215, v223
	ds_bpermute_b32 v226, v215, v225
	s_waitcnt lgkmcnt(4)
	v_add_f32_e32 v207, v207, v227
	s_waitcnt lgkmcnt(3)
	v_add_f32_e32 v231, v230, v231
	ds_bpermute_b32 v227, v214, v207
	ds_bpermute_b32 v234, v214, v231
	s_waitcnt lgkmcnt(4)
	v_add_f32_e32 v228, v228, v229
	ds_bpermute_b32 v229, v211, v228
	s_waitcnt lgkmcnt(2)
	v_add_f32_e32 v227, v207, v227
	s_waitcnt lgkmcnt(1)
	v_add_f32_e32 v231, v231, v234
	v_mul_f32_e32 v207, v175, v81
	v_mul_f32_e32 v234, v173, v83
	v_fmac_f32_e32 v207, v174, v80
	v_fmac_f32_e32 v234, v172, v82
	v_add_f32_e32 v207, v207, v234
	v_mul_f32_e32 v234, v171, v85
	v_fmac_f32_e32 v234, v170, v84
	v_add_f32_e32 v207, 0, v207
	v_add_f32_e32 v234, v234, v235
	v_add_f32_e32 v207, v207, v234
	v_mul_f32_e32 v234, v167, v89
	v_mul_f32_e32 v235, v165, v91
	v_fmac_f32_e32 v234, v166, v88
	v_fmac_f32_e32 v235, v164, v90
	v_add_f32_e32 v234, v234, v235
	v_add_f32_e32 v207, v207, v234
	v_mul_f32_e32 v234, v163, v93
	v_mul_f32_e32 v235, v161, v95
	v_fmac_f32_e32 v234, v162, v92
	v_fmac_f32_e32 v235, v160, v94
	v_add_f32_e32 v234, v234, v235
	v_mul_f32_e32 v235, v175, v97
	v_fmac_f32_e32 v235, v174, v96
	v_add_f32_e32 v235, v235, v236
	v_mul_f32_e32 v236, v171, v101
	v_fmac_f32_e32 v236, v170, v100
	v_add_f32_e32 v235, 0, v235
	v_add_f32_e32 v236, v236, v237
	v_add_f32_e32 v235, v235, v236
	v_mul_f32_e32 v236, v167, v105
	v_mul_f32_e32 v237, v165, v107
	v_fmac_f32_e32 v236, v166, v104
	v_fmac_f32_e32 v237, v164, v106
	v_mul_f32_e32 v175, v175, v113
	v_mul_f32_e32 v173, v173, v115
	v_add_f32_e32 v236, v236, v237
	v_fmac_f32_e32 v175, v174, v112
	v_fmac_f32_e32 v173, v172, v114
	v_mul_f32_e32 v171, v171, v117
	v_add_f32_e32 v235, v235, v236
	v_mul_f32_e32 v236, v163, v109
	v_add_f32_e32 v172, v175, v173
	v_fmac_f32_e32 v171, v170, v116
	v_mul_f32_e32 v167, v167, v121
	v_mul_f32_e32 v165, v165, v123
	v_mul_f32_e32 v163, v163, v125
	v_fmac_f32_e32 v236, v162, v108
	v_mul_f32_e32 v237, v161, v111
	v_add_f32_e32 v172, 0, v172
	v_add_f32_e32 v168, v171, v169
	v_fmac_f32_e32 v167, v166, v120
	v_fmac_f32_e32 v165, v164, v122
	v_fmac_f32_e32 v163, v162, v124
	v_mul_f32_e32 v162, v161, v127
	v_fmac_f32_e32 v237, v160, v110
	v_add_f32_e32 v168, v172, v168
	v_add_f32_e32 v164, v167, v165
	v_fmac_f32_e32 v162, v160, v126
	v_add_f32_e32 v236, v236, v237
	v_add_f32_e32 v164, v168, v164
	v_add_f32_e32 v160, v163, v162
	v_add_f32_e32 v207, v207, v234
	v_add_f32_e32 v235, v235, v236
	v_add_f32_e32 v160, v164, v160
	ds_bpermute_b32 v234, v209, v207
	ds_bpermute_b32 v236, v209, v235
	ds_bpermute_b32 v162, v209, v160
	s_waitcnt lgkmcnt(3)
	v_add_f32_e32 v228, v228, v229
	ds_bpermute_b32 v229, v212, v228
	s_waitcnt lgkmcnt(3)
	v_add_f32_e32 v163, v207, v234
	s_waitcnt lgkmcnt(2)
	v_add_f32_e32 v165, v235, v236
	s_waitcnt lgkmcnt(1)
	v_add_f32_e32 v160, v160, v162
	ds_bpermute_b32 v164, v211, v163
	ds_bpermute_b32 v166, v211, v165
	ds_bpermute_b32 v162, v211, v160
	s_waitcnt lgkmcnt(3)
	v_add_f32_e32 v228, v228, v229
	ds_bpermute_b32 v229, v213, v228
	s_waitcnt lgkmcnt(3)
	v_add_f32_e32 v163, v163, v164
	s_waitcnt lgkmcnt(2)
	v_add_f32_e32 v165, v165, v166
	s_waitcnt lgkmcnt(1)
	v_add_f32_e32 v160, v160, v162
	ds_bpermute_b32 v164, v212, v163
	ds_bpermute_b32 v166, v212, v165
	ds_bpermute_b32 v162, v212, v160
	s_waitcnt lgkmcnt(3)
	v_add_f32_e32 v229, v228, v229
	ds_bpermute_b32 v232, v214, v229
	s_waitcnt lgkmcnt(3)
	v_add_f32_e32 v163, v163, v164
	s_waitcnt lgkmcnt(2)
	v_add_f32_e32 v165, v165, v166
	s_waitcnt lgkmcnt(1)
	v_add_f32_e32 v160, v160, v162
	ds_bpermute_b32 v164, v213, v163
	ds_bpermute_b32 v166, v213, v165
	ds_bpermute_b32 v162, v213, v160
	s_waitcnt lgkmcnt(3)
	v_add_f32_e32 v229, v229, v232
	ds_bpermute_b32 v228, v215, v227
	s_waitcnt lgkmcnt(3)
	v_add_f32_e32 v163, v163, v164
	s_waitcnt lgkmcnt(2)
	v_add_f32_e32 v165, v165, v166
	s_waitcnt lgkmcnt(1)
	v_add_f32_e32 v167, v160, v162
	ds_bpermute_b32 v164, v214, v163
	ds_bpermute_b32 v166, v214, v165
	ds_bpermute_b32 v168, v214, v167
	ds_bpermute_b32 v230, v215, v229
	ds_bpermute_b32 v232, v215, v231
	s_waitcnt lgkmcnt(4)
	v_add_f32_e32 v160, v163, v164
	s_waitcnt lgkmcnt(3)
	v_add_f32_e32 v163, v165, v166
	s_waitcnt lgkmcnt(2)
	v_add_f32_e32 v165, v167, v168
	ds_bpermute_b32 v162, v215, v160
	ds_bpermute_b32 v164, v215, v163
	ds_bpermute_b32 v166, v215, v165
	v_bfe_u32 v167, v161, 16, 1
	v_add3_u32 v161, v161, v167, s42
	v_and_or_b32 v207, v161, s43, v233
	global_store_dwordx2 v[186:187], v[206:207], off offset:512
	s_and_saveexec_b64 s[36:37], s[4:5]
	s_cbranch_execz .LBB0_401
	v_mov_b32_e32 v161, v255
	v_add_f32_e32 v167, v225, v226
	v_add_f32_e32 v168, v223, v224
	s_waitcnt lgkmcnt(0)
	v_add_f32_e32 v165, v165, v166
	v_add_f32_e32 v166, v227, v228
	v_cndmask_b32_e64 v167, v168, v167, s[18:19]
	v_add_f32_e32 v163, v163, v164
	v_add_f32_e32 v164, v229, v230
	v_cndmask_b32_e64 v166, v167, v166, s[16:17]
	v_add_f32_e32 v160, v160, v162
	v_add_f32_e32 v162, v231, v232
	v_cndmask_b32_e64 v164, v166, v164, s[14:15]
	v_cndmask_b32_e64 v162, v164, v162, s[12:13]
	v_cndmask_b32_e64 v160, v162, v160, s[10:11]
	v_cndmask_b32_e64 v160, v160, v163, s[8:9]
	v_cndmask_b32_e64 v160, v160, v165, s[6:7]
	v_add_f32_e32 v160, v160, v161
	v_mul_f32_e64 v161, |v160|, s48
	v_exp_f32_e32 v161, v161
	v_min_f32_e32 v160, 0, v160
	v_add_f32_e32 v161, 1.0, v161
	v_cmp_gt_f32_e32 vcc, s49, v161
	s_nop 1
	v_cndmask_b32_e64 v162, 0, 32, vcc
	v_ldexp_f32 v161, v161, v162
	v_log_f32_e32 v161, v161
	s_nop 0
	v_mul_f32_e32 v162, 0x3f317217, v161
	v_fma_f32 v162, v161, s52, -v162
	v_fmac_f32_e32 v162, 0x3377d1cf, v161
	v_fmac_f32_e32 v162, 0x3f317217, v161
	v_cmp_lt_f32_e64 s[0:1], |v161|, s53
	s_nop 1
	v_cndmask_b32_e64 v161, v161, v162, s[0:1]
	v_cndmask_b32_e32 v162, 0, v222, vcc
	v_sub_f32_e32 v161, v161, v162
	v_sub_f32_e32 v160, v160, v161
	global_store_dword v[188:189], v160, off
	s_branch .LBB0_401

.LBB0_494:
	s_ashr_i32 s26, s0, 1
	s_ashr_i32 s27, s26, 31
	s_lshl_b64 s[28:29], s[26:27], 26
	s_add_u32 s28, s40, s28
	v_lshl_add_u32 v128, s6, 8, v147
	s_addc_u32 s29, s41, s29
	v_ashrrev_i32_e32 v129, 31, v128
	s_lshl_b32 s1, s0, 8
	v_lshlrev_b64 v[128:129], 10, v[128:129]
	s_and_b32 s1, s1, 0x100
	v_lshl_add_u64 v[128:129], s[28:29], 0, v[128:129]
	s_lshl_b32 s8, s1, 1
	v_lshl_add_u64 v[158:159], v[128:129], 0, s[8:9]
	s_cmp_gt_i32 s26, 1
	s_mov_b64 s[6:7], -1
	s_cbranch_scc0 .LBB0_506
	s_cmp_eq_u32 s26, 4
	v_or_b32_e32 v128, s1, v148
	s_cselect_b64 s[28:29], -1, 0
	s_cmp_lg_u32 s26, 4
	v_mov_b32_e32 v170, 1.0
	v_lshlrev_b32_e32 v128, 2, v128
	v_mov_b32_e32 v172, 1.0
	v_mov_b32_e32 v173, 1.0
	v_mov_b32_e32 v174, 1.0
	v_mov_b32_e32 v175, 1.0
	s_cbranch_scc1 .LBB0_497
	global_load_dwordx4 v[130:133], v128, s[50:51]
	global_load_dwordx4 v[160:163], v128, s[50:51] offset:2048
	global_load_dwordx4 v[212:215], v128, s[50:51] offset:16
	global_load_dwordx4 v[216:219], v128, s[50:51] offset:2064
	global_load_dwordx4 v[220:223], v128, s[50:51] offset:512
	global_load_dwordx4 v[224:227], v128, s[50:51] offset:2560
	global_load_dwordx4 v[228:231], v128, s[50:51] offset:528
	global_load_dwordx4 v[232:235], v128, s[50:51] offset:2576
	s_waitcnt vmcnt(0)
	v_sub_f32_e32 v129, v130, v160
	v_sub_f32_e32 v130, v131, v161
	v_sub_f32_e32 v131, v132, v162
	v_sub_f32_e32 v132, v133, v163
	v_mul_f32_e32 v129, 0x3fb8aa3b, v129
	v_mul_f32_e32 v130, 0x3fb8aa3b, v130
	v_mul_f32_e32 v131, 0x3fb8aa3b, v131
	v_mul_f32_e32 v132, 0x3fb8aa3b, v132
	v_exp_f32_e32 v129, v129
	v_exp_f32_e32 v130, v130
	v_exp_f32_e32 v131, v131
	v_exp_f32_e32 v132, v132
	v_add_f32_e32 v129, 1.0, v129
	v_add_f32_e32 v130, 1.0, v130
	v_add_f32_e32 v131, 1.0, v131
	v_add_f32_e32 v132, 1.0, v132
	v_rcp_f32_e32 v172, v129
	v_rcp_f32_e32 v173, v130
	v_rcp_f32_e32 v174, v131
	v_rcp_f32_e32 v175, v132
.LBB0_497:
	v_cndmask_b32_e64 v129, 0, 1, s[28:29]
	v_cmp_ne_u32_e64 s[6:7], 1, v129
	s_andn2_b64 vcc, exec, s[28:29]
	v_mov_b32_e32 v171, 1.0
	v_mov_b32_e32 v176, 1.0
	v_mov_b32_e32 v177, 1.0
	s_cbranch_vccnz .LBB0_499
	v_sub_f32_e32 v129, v212, v216
	v_sub_f32_e32 v130, v213, v217
	v_sub_f32_e32 v131, v214, v218
	v_sub_f32_e32 v132, v215, v219
	v_mul_f32_e32 v129, 0x3fb8aa3b, v129
	v_mul_f32_e32 v130, 0x3fb8aa3b, v130
	v_mul_f32_e32 v131, 0x3fb8aa3b, v131
	v_mul_f32_e32 v132, 0x3fb8aa3b, v132
	v_exp_f32_e32 v129, v129
	v_exp_f32_e32 v130, v130
	v_exp_f32_e32 v131, v131
	v_exp_f32_e32 v132, v132
	v_add_f32_e32 v129, 1.0, v129
	v_add_f32_e32 v130, 1.0, v130
	v_add_f32_e32 v131, 1.0, v131
	v_add_f32_e32 v132, 1.0, v132
	v_rcp_f32_e32 v170, v129
	v_rcp_f32_e32 v171, v130
	v_rcp_f32_e32 v176, v131
	v_rcp_f32_e32 v177, v132
.LBB0_499:
	v_mov_b32_e32 v160, 1.0
	s_and_b64 vcc, exec, s[6:7]
	v_mov_b32_e32 v162, 1.0
	v_mov_b32_e32 v163, 1.0
	v_mov_b32_e32 v164, 1.0
	v_mov_b32_e32 v165, 1.0
	s_cbranch_vccnz .LBB0_501
	v_sub_f32_e32 v129, v220, v224
	v_sub_f32_e32 v130, v221, v225
	v_sub_f32_e32 v131, v222, v226
	v_sub_f32_e32 v132, v223, v227
	v_mul_f32_e32 v129, 0x3fb8aa3b, v129
	v_mul_f32_e32 v130, 0x3fb8aa3b, v130
	v_mul_f32_e32 v131, 0x3fb8aa3b, v131
	v_mul_f32_e32 v132, 0x3fb8aa3b, v132
	v_exp_f32_e32 v129, v129
	v_exp_f32_e32 v130, v130
	v_exp_f32_e32 v131, v131
	v_exp_f32_e32 v132, v132
	v_add_f32_e32 v129, 1.0, v129
	v_add_f32_e32 v130, 1.0, v130
	v_add_f32_e32 v131, 1.0, v131
	v_add_f32_e32 v132, 1.0, v132
	v_rcp_f32_e32 v162, v129
	v_rcp_f32_e32 v163, v130
	v_rcp_f32_e32 v164, v131
	v_rcp_f32_e32 v165, v132
.LBB0_501:
	s_and_b64 vcc, exec, s[6:7]
	v_mov_b32_e32 v161, 1.0
	v_mov_b32_e32 v166, 1.0
	v_mov_b32_e32 v167, 1.0
	s_cbranch_vccnz .LBB0_503
	v_sub_f32_e32 v128, v228, v232
	v_sub_f32_e32 v129, v229, v233
	v_sub_f32_e32 v130, v230, v234
	v_sub_f32_e32 v131, v231, v235
	v_mul_f32_e32 v128, 0x3fb8aa3b, v128
	v_mul_f32_e32 v129, 0x3fb8aa3b, v129
	v_mul_f32_e32 v130, 0x3fb8aa3b, v130
	v_mul_f32_e32 v131, 0x3fb8aa3b, v131
	v_exp_f32_e32 v128, v128
	v_exp_f32_e32 v129, v129
	v_exp_f32_e32 v130, v130
	v_exp_f32_e32 v131, v131
	v_add_f32_e32 v128, 1.0, v128
	v_add_f32_e32 v129, 1.0, v129
	v_add_f32_e32 v130, 1.0, v130
	v_add_f32_e32 v131, 1.0, v131
	v_rcp_f32_e32 v160, v128
	v_rcp_f32_e32 v161, v129
	v_rcp_f32_e32 v166, v130
	v_rcp_f32_e32 v167, v131
